# GEMM k-loops: DMA address math hoisted above the barrier; six LDS-DMA issues spread between MFMAs (after MFMA 4,9,14,19,24,29) instead of a burst after the barrier
# speedup vs baseline: 1.1233x; 1.0318x over previous
; __device__ __forceinline__ void lds_barrier() { asm volatile("s_waitcnt lgkmcnt(0)\n\ts_barrier" ::: "memory"); }
; template <int EPI>
; __device__ void gemm_phase(const u16* __restrict__ A, const u16* __restrict__ Bt, void* __restrict__ Cv,
;                            int N, int K, int ldc, unsigned char* ldsraw, int G) {
;     ...
;     for (int kt = 0; kt < nk; ++kt) {
;       asm volatile("s_waitcnt vmcnt(6)" ::: "memory");
;       lds_barrier();
;       const int st2 = (st >= 1) ? st - 1 : 2;
;       GLDS(st2, kt + 2);
;       const u16* Asx = As + st * STG;
;       const u16* Bsx = Asx + GBM * GLD;
; #pragma unroll
;       for (int ks = 0; ks < 2; ++ks) {
;         const int fsw = ((ks * 4 + g4) ^ fx) * 8;
;         bf16x8 bfr[4];
; #pragma unroll
;         for (int jx = 0; jx < 4; ++jx) bfr[jx] = *(const bf16x8*)(Bsx + (wn * 64 + jx * 16 + l15) * GLD + fsw);
; #pragma unroll
;         for (int ix = 0; ix < 4; ++ix) {
;           const bf16x8 af = *(const bf16x8*)(Asx + (wm * 64 + ix * 16 + l15) * GLD + fsw);
; #pragma unroll
;           for (int jx = 0; jx < 4; ++jx)
;             acc[ix][jx] = __builtin_amdgcn_mfma_f32_16x16x32_bf16(af, bfr[jx], acc[ix][jx], 0, 0, 0);
;         }
;       }
;       st = (st == 2) ? 0 : st + 1;
;     }
;     ...
;     for (int i = 0; i < 4; ++i) {
; #pragma unroll
;       for (int r = 0; r < 4; ++r) {
;         const int m = m0 + wm * 64 + i * 16 + g4 * 4 + r;
;         const int nb = n0 + wn * 64 + l15;
;         if (EPI == EPI_F32) {
;           float* cp = (float*)Cv + (size_t)m * ldc + nb;
; #pragma unroll
;           for (int j = 0; j < 4; ++j) if (nb + j * 16 < N) cp[j * 16] = acc[i][j][r];
;         } else {
;           u16* cp = (u16*)Cv + (size_t)m * ldc + nb;
; #pragma unroll
;           for (int j = 0; j < 4; ++j) {
;             float v = acc[i][j][r];
;             if (EPI == EPI_RELU2) { v = fmaxf(v, 0.f); v = v * v; }
;             if (nb + j * 16 < N) cp[j * 16] = f2bf(v);
.LBB0_20:
	s_mul_i32 s8, s5, 0xc000
	s_min_u32 s7, s6, 61
	s_add_i32 s9, s8, 0xffff4000
	s_cmp_gt_i32 s5, 0
	s_waitcnt vmcnt(6)
	s_cselect_b32 s9, s9, 0x18000
	s_lshl_b32 s98, s7, 7
	s_add_i32 s7, s8, 0x100
	s_add_i32 s8, s9, s4
	s_add_i32 s9, s8, 0x2000
	s_add_i32 s11, s8, 0x4000
	s_add_i32 s12, s8, 0x6000
	s_add_i32 s13, s8, 0x8000
	s_add_i32 s14, s8, 0xa000
	v_lshl_add_u64 v[236:237], v[76:77], 0, s[98:99]
	v_lshl_add_u64 v[238:239], v[80:81], 0, s[98:99]
	v_lshl_add_u64 v[236:237], v[236:237], 0, s[42:43]
	v_lshl_add_u64 v[240:241], v[82:83], 0, s[98:99]
	v_lshl_add_u64 v[238:239], v[238:239], 0, s[42:43]
	v_lshl_add_u64 v[242:243], v[84:85], 0, s[98:99]
	v_lshl_add_u64 v[240:241], v[240:241], 0, s[42:43]
	v_lshl_add_u64 v[244:245], v[78:79], 0, s[98:99]
	v_lshl_add_u64 v[242:243], v[242:243], 0, s[42:43]
	v_lshl_add_u64 v[246:247], v[86:87], 0, s[98:99]
	v_lshl_add_u64 v[244:245], v[244:245], 0, s[42:43]
	v_lshl_add_u64 v[246:247], v[246:247], 0, s[42:43]
	v_lshl_add_u32 v109, v104, 1, s7
	v_add3_u32 v130, v109, v105, v106
	v_add3_u32 v109, v109, v107, v106
	s_waitcnt lgkmcnt(0)
	s_barrier
	s_mov_b32 s15, m0
	ds_read_b128 v[110:113], v109
	ds_read_b128 v[114:117], v130 offset:32768
	ds_read_b128 v[118:121], v130 offset:34816
	ds_read_b128 v[122:125], v109 offset:2048
	ds_read_b128 v[126:129], v130 offset:36864
	ds_read_b128 v[130:133], v130 offset:38912
	s_waitcnt lgkmcnt(4)
	v_mfma_f32_16x16x32_bf16 v[64:67], v[110:113], v[114:117], v[64:67]
	s_waitcnt lgkmcnt(3)
	v_mfma_f32_16x16x32_bf16 v[60:63], v[110:113], v[118:121], v[60:63]
	s_waitcnt lgkmcnt(1)
	v_mfma_f32_16x16x32_bf16 v[56:59], v[110:113], v[126:129], v[56:59]
	s_waitcnt lgkmcnt(0)
	s_mov_b32 m0, s8
	v_mfma_f32_16x16x32_bf16 v[52:55], v[110:113], v[130:133], v[52:55]
	global_load_lds_dwordx4 v[236:237], off
	v_mfma_f32_16x16x32_bf16 v[48:51], v[122:125], v[114:117], v[48:51]
	v_mfma_f32_16x16x32_bf16 v[44:47], v[122:125], v[118:121], v[44:47]
	v_mfma_f32_16x16x32_bf16 v[40:43], v[122:125], v[126:129], v[40:43]
	v_mfma_f32_16x16x32_bf16 v[36:39], v[122:125], v[130:133], v[36:39]
	ds_read_b128 v[110:113], v109 offset:4096
	ds_read_b128 v[122:125], v109 offset:6144
	v_lshl_add_u32 v109, v108, 1, s7
	v_add3_u32 v134, v109, v105, v106
	v_add3_u32 v109, v109, v107, v106
	s_waitcnt lgkmcnt(1)
	s_mov_b32 m0, s9
	v_mfma_f32_16x16x32_bf16 v[32:35], v[110:113], v[114:117], v[32:35]
	global_load_lds_dwordx4 v[238:239], off
	s_add_i32 s7, s5, 1
	s_cmp_lg_u32 s5, 2
	s_cselect_b32 s5, s7, 0
	v_mfma_f32_16x16x32_bf16 v[28:31], v[110:113], v[118:121], v[28:31]
	s_add_i32 s6, s6, 1
	s_cmp_eq_u32 s6, 64
	v_mfma_f32_16x16x32_bf16 v[24:27], v[110:113], v[126:129], v[24:27]
	v_mfma_f32_16x16x32_bf16 v[20:23], v[110:113], v[130:133], v[20:23]
	ds_read_b128 v[110:113], v109
	s_waitcnt lgkmcnt(1)
	v_mfma_f32_16x16x32_bf16 v[16:19], v[122:125], v[114:117], v[16:19]
	s_mov_b32 m0, s11
	v_mfma_f32_16x16x32_bf16 v[12:15], v[122:125], v[118:121], v[12:15]
	global_load_lds_dwordx4 v[240:241], off
	v_mfma_f32_16x16x32_bf16 v[8:11], v[122:125], v[126:129], v[8:11]
	v_mfma_f32_16x16x32_bf16 v[2:5], v[122:125], v[130:133], v[2:5]
	ds_read_b128 v[114:117], v134 offset:32768
	ds_read_b128 v[118:121], v134 offset:34816
	ds_read_b128 v[122:125], v109 offset:2048
	ds_read_b128 v[126:129], v134 offset:36864
	ds_read_b128 v[130:133], v134 offset:38912
	s_waitcnt lgkmcnt(4)
	v_mfma_f32_16x16x32_bf16 v[64:67], v[110:113], v[114:117], v[64:67]
	s_waitcnt lgkmcnt(3)
	v_mfma_f32_16x16x32_bf16 v[60:63], v[110:113], v[118:121], v[60:63]
	s_waitcnt lgkmcnt(1)
	s_mov_b32 m0, s12
	v_mfma_f32_16x16x32_bf16 v[56:59], v[110:113], v[126:129], v[56:59]
	global_load_lds_dwordx4 v[242:243], off
	s_waitcnt lgkmcnt(0)
	v_mfma_f32_16x16x32_bf16 v[52:55], v[110:113], v[130:133], v[52:55]
	v_mfma_f32_16x16x32_bf16 v[48:51], v[122:125], v[114:117], v[48:51]
	v_mfma_f32_16x16x32_bf16 v[44:47], v[122:125], v[118:121], v[44:47]
	v_mfma_f32_16x16x32_bf16 v[40:43], v[122:125], v[126:129], v[40:43]
	s_mov_b32 m0, s13
	v_mfma_f32_16x16x32_bf16 v[36:39], v[122:125], v[130:133], v[36:39]
	global_load_lds_dwordx4 v[244:245], off
	ds_read_b128 v[110:113], v109 offset:4096
	ds_read_b128 v[122:125], v109 offset:6144
	s_waitcnt lgkmcnt(1)
	v_mfma_f32_16x16x32_bf16 v[32:35], v[110:113], v[114:117], v[32:35]
	v_mfma_f32_16x16x32_bf16 v[28:31], v[110:113], v[118:121], v[28:31]
	v_mfma_f32_16x16x32_bf16 v[24:27], v[110:113], v[126:129], v[24:27]
	v_mfma_f32_16x16x32_bf16 v[20:23], v[110:113], v[130:133], v[20:23]
	s_waitcnt lgkmcnt(0)
	s_mov_b32 m0, s14
	v_mfma_f32_16x16x32_bf16 v[16:19], v[122:125], v[114:117], v[16:19]
	global_load_lds_dwordx4 v[246:247], off
	s_mov_b32 m0, s15
	v_mfma_f32_16x16x32_bf16 v[12:15], v[122:125], v[118:121], v[12:15]
	v_mfma_f32_16x16x32_bf16 v[8:11], v[122:125], v[126:129], v[8:11]
	v_mfma_f32_16x16x32_bf16 v[2:5], v[122:125], v[130:133], v[2:5]
	s_cbranch_scc0 .LBB0_20
	s_setprio 0
	s_waitcnt vmcnt(0)
	v_add_u32_e32 v78, s0, v0
	v_or_b32_e32 v82, s1, v75
	s_waitcnt lgkmcnt(0)
	s_barrier
	v_ashrrev_i32_e32 v83, 31, v82
	v_ashrrev_i32_e32 v79, 31, v78
	v_lshl_add_u64 v[76:77], v[82:83], 1, s[76:77]
	v_lshlrev_b64 v[80:81], 11, v[78:79]
	s_movk_i32 s0, 0x400
	v_lshl_add_u64 v[80:81], v[76:77], 0, v[80:81]
	v_cmp_gt_i32_e32 vcc, s0, v82
	s_and_saveexec_b64 s[0:1], vcc
	s_cbranch_execz .LBB0_23
	v_bfe_u32 v79, v64, 16, 1
	v_add3_u32 v64, v64, v79, s96
	global_store_short_d16_hi v[80:81], v64, off

; __device__ __forceinline__ void lds_barrier() { asm volatile("s_waitcnt lgkmcnt(0)\n\ts_barrier" ::: "memory"); }
; template <int EPI>
; __device__ void gemm_phase(const u16* __restrict__ A, const u16* __restrict__ Bt, void* __restrict__ Cv,
;                            int N, int K, int ldc, unsigned char* ldsraw, int G) {
;     ...
;     for (int kt = 0; kt < nk; ++kt) {
;       asm volatile("s_waitcnt vmcnt(6)" ::: "memory");
;       lds_barrier();
;       const int st2 = (st >= 1) ? st - 1 : 2;
;       GLDS(st2, kt + 2);
;       const u16* Asx = As + st * STG;
;       const u16* Bsx = Asx + GBM * GLD;
; #pragma unroll
;       for (int ks = 0; ks < 2; ++ks) {
;         const int fsw = ((ks * 4 + g4) ^ fx) * 8;
;         bf16x8 bfr[4];
; #pragma unroll
;         for (int jx = 0; jx < 4; ++jx) bfr[jx] = *(const bf16x8*)(Bsx + (wn * 64 + jx * 16 + l15) * GLD + fsw);
; #pragma unroll
;         for (int ix = 0; ix < 4; ++ix) {
;           const bf16x8 af = *(const bf16x8*)(Asx + (wm * 64 + ix * 16 + l15) * GLD + fsw);
; #pragma unroll
;           for (int jx = 0; jx < 4; ++jx)
;             acc[ix][jx] = __builtin_amdgcn_mfma_f32_16x16x32_bf16(af, bfr[jx], acc[ix][jx], 0, 0, 0);
;         }
;       }
;       st = (st == 2) ? 0 : st + 1;
;     }
;     ...
;           u16* cp = (u16*)Cv + (size_t)m * ldc + nb;
; #pragma unroll
;           for (int j = 0; j < 4; ++j) {
;             float v = acc[i][j][r];
;             if (EPI == EPI_RELU2) { v = fmaxf(v, 0.f); v = v * v; }
;             if (nb + j * 16 < N) cp[j * 16] = f2bf(v);
;           }
.LBB0_157:
	s_mul_i32 s9, s6, 0xc000
	s_min_u32 s8, s7, 13
	s_add_i32 s10, s9, 0xffff4000
	s_cmp_gt_i32 s6, 0
	s_waitcnt vmcnt(6)
	s_cselect_b32 s10, s10, 0x18000
	s_lshl_b32 s98, s8, 7
	s_add_i32 s8, s9, 0x100
	s_add_i32 s9, s10, s5
	s_add_i32 s10, s9, 0x2000
	s_add_i32 s11, s9, 0x4000
	s_add_i32 s12, s9, 0x6000
	s_add_i32 s13, s9, 0x8000
	s_add_i32 s14, s9, 0xa000
	v_lshl_add_u64 v[236:237], v[76:77], 0, s[98:99]
	v_lshl_add_u64 v[238:239], v[80:81], 0, s[98:99]
	v_lshl_add_u64 v[236:237], v[236:237], 0, s[42:43]
	v_lshl_add_u64 v[240:241], v[82:83], 0, s[98:99]
	v_lshl_add_u64 v[238:239], v[238:239], 0, s[42:43]
	v_lshl_add_u64 v[242:243], v[84:85], 0, s[98:99]
	v_lshl_add_u64 v[240:241], v[240:241], 0, s[42:43]
	v_lshl_add_u64 v[244:245], v[78:79], 0, s[98:99]
	v_lshl_add_u64 v[242:243], v[242:243], 0, s[42:43]
	v_lshl_add_u64 v[246:247], v[86:87], 0, s[98:99]
	v_lshl_add_u64 v[244:245], v[244:245], 0, s[42:43]
	v_lshl_add_u64 v[246:247], v[246:247], 0, s[42:43]
	v_lshl_add_u32 v109, v104, 1, s8
	v_add3_u32 v130, v109, v105, v106
	v_add3_u32 v109, v109, v107, v106
	s_waitcnt lgkmcnt(0)
	s_barrier
	s_mov_b32 s15, m0
	ds_read_b128 v[110:113], v109
	ds_read_b128 v[114:117], v130 offset:32768
	ds_read_b128 v[118:121], v130 offset:34816
	ds_read_b128 v[122:125], v109 offset:2048
	ds_read_b128 v[126:129], v130 offset:36864
	ds_read_b128 v[130:133], v130 offset:38912
	s_waitcnt lgkmcnt(4)
	v_mfma_f32_16x16x32_bf16 v[64:67], v[110:113], v[114:117], v[64:67]
	s_waitcnt lgkmcnt(3)
	v_mfma_f32_16x16x32_bf16 v[60:63], v[110:113], v[118:121], v[60:63]
	s_waitcnt lgkmcnt(1)
	v_mfma_f32_16x16x32_bf16 v[56:59], v[110:113], v[126:129], v[56:59]
	s_waitcnt lgkmcnt(0)
	s_mov_b32 m0, s9
	v_mfma_f32_16x16x32_bf16 v[52:55], v[110:113], v[130:133], v[52:55]
	global_load_lds_dwordx4 v[236:237], off
	v_mfma_f32_16x16x32_bf16 v[48:51], v[122:125], v[114:117], v[48:51]
	v_mfma_f32_16x16x32_bf16 v[44:47], v[122:125], v[118:121], v[44:47]
	v_mfma_f32_16x16x32_bf16 v[40:43], v[122:125], v[126:129], v[40:43]
	v_mfma_f32_16x16x32_bf16 v[36:39], v[122:125], v[130:133], v[36:39]
	ds_read_b128 v[110:113], v109 offset:4096
	ds_read_b128 v[122:125], v109 offset:6144
	v_lshl_add_u32 v109, v108, 1, s8
	v_add3_u32 v134, v109, v105, v106
	v_add3_u32 v109, v109, v107, v106
	s_waitcnt lgkmcnt(1)
	s_mov_b32 m0, s10
	v_mfma_f32_16x16x32_bf16 v[32:35], v[110:113], v[114:117], v[32:35]
	global_load_lds_dwordx4 v[238:239], off
	s_add_i32 s8, s6, 1
	s_cmp_lg_u32 s6, 2
	s_cselect_b32 s6, s8, 0
	v_mfma_f32_16x16x32_bf16 v[28:31], v[110:113], v[118:121], v[28:31]
	s_add_i32 s7, s7, 1
	s_cmp_eq_u32 s7, 16
	v_mfma_f32_16x16x32_bf16 v[24:27], v[110:113], v[126:129], v[24:27]
	v_mfma_f32_16x16x32_bf16 v[20:23], v[110:113], v[130:133], v[20:23]
	ds_read_b128 v[110:113], v109
	s_waitcnt lgkmcnt(1)
	v_mfma_f32_16x16x32_bf16 v[16:19], v[122:125], v[114:117], v[16:19]
	s_mov_b32 m0, s11
	v_mfma_f32_16x16x32_bf16 v[12:15], v[122:125], v[118:121], v[12:15]
	global_load_lds_dwordx4 v[240:241], off
	v_mfma_f32_16x16x32_bf16 v[8:11], v[122:125], v[126:129], v[8:11]
	v_mfma_f32_16x16x32_bf16 v[2:5], v[122:125], v[130:133], v[2:5]
	ds_read_b128 v[114:117], v134 offset:32768
	ds_read_b128 v[118:121], v134 offset:34816
	ds_read_b128 v[122:125], v109 offset:2048
	ds_read_b128 v[126:129], v134 offset:36864
	ds_read_b128 v[130:133], v134 offset:38912
	s_waitcnt lgkmcnt(4)
	v_mfma_f32_16x16x32_bf16 v[64:67], v[110:113], v[114:117], v[64:67]
	s_waitcnt lgkmcnt(3)
	v_mfma_f32_16x16x32_bf16 v[60:63], v[110:113], v[118:121], v[60:63]
	s_waitcnt lgkmcnt(1)
	s_mov_b32 m0, s12
	v_mfma_f32_16x16x32_bf16 v[56:59], v[110:113], v[126:129], v[56:59]
	global_load_lds_dwordx4 v[242:243], off
	s_waitcnt lgkmcnt(0)
	v_mfma_f32_16x16x32_bf16 v[52:55], v[110:113], v[130:133], v[52:55]
	v_mfma_f32_16x16x32_bf16 v[48:51], v[122:125], v[114:117], v[48:51]
	v_mfma_f32_16x16x32_bf16 v[44:47], v[122:125], v[118:121], v[44:47]
	v_mfma_f32_16x16x32_bf16 v[40:43], v[122:125], v[126:129], v[40:43]
	s_mov_b32 m0, s13
	v_mfma_f32_16x16x32_bf16 v[36:39], v[122:125], v[130:133], v[36:39]
	global_load_lds_dwordx4 v[244:245], off
	ds_read_b128 v[110:113], v109 offset:4096
	ds_read_b128 v[122:125], v109 offset:6144
	s_waitcnt lgkmcnt(1)
	v_mfma_f32_16x16x32_bf16 v[32:35], v[110:113], v[114:117], v[32:35]
	v_mfma_f32_16x16x32_bf16 v[28:31], v[110:113], v[118:121], v[28:31]
	v_mfma_f32_16x16x32_bf16 v[24:27], v[110:113], v[126:129], v[24:27]
	v_mfma_f32_16x16x32_bf16 v[20:23], v[110:113], v[130:133], v[20:23]
	s_waitcnt lgkmcnt(0)
	s_mov_b32 m0, s14
	v_mfma_f32_16x16x32_bf16 v[16:19], v[122:125], v[114:117], v[16:19]
	global_load_lds_dwordx4 v[246:247], off
	s_mov_b32 m0, s15
	v_mfma_f32_16x16x32_bf16 v[12:15], v[122:125], v[118:121], v[12:15]
	v_mfma_f32_16x16x32_bf16 v[8:11], v[122:125], v[126:129], v[8:11]
	v_mfma_f32_16x16x32_bf16 v[2:5], v[122:125], v[130:133], v[2:5]
	s_cbranch_scc0 .LBB0_157
	s_setprio 0
	v_max_f32_e32 v64, v64, v64
	v_add_u32_e32 v78, s1, v0
	v_or_b32_e32 v76, s4, v75
	v_max_f32_e32 v64, 0, v64
	v_ashrrev_i32_e32 v77, 31, v76
	v_ashrrev_i32_e32 v79, 31, v78
	v_mul_f32_e32 v64, v64, v64
	v_max_f32_e32 v60, v60, v60
	v_lshl_add_u64 v[76:77], v[76:77], 1, s[18:19]
	v_lshlrev_b64 v[80:81], 13, v[78:79]
	v_bfe_u32 v79, v64, 16, 1
	v_max_f32_e32 v60, 0, v60
	s_waitcnt vmcnt(0)
	v_lshl_add_u64 v[80:81], v[76:77], 0, v[80:81]
	v_add3_u32 v64, v64, v79, s96
	v_mul_f32_e32 v60, v60, v60
	v_max_f32_e32 v56, v56, v56
	s_waitcnt lgkmcnt(0)
	s_barrier
; template <int EPI>
; __device__ void gemm_phase(const u16* __restrict__ A, const u16* __restrict__ Bt, void* __restrict__ Cv,
;                            int N, int K, int ldc, unsigned char* ldsraw, int G) {
;     ...
;     for (int i = 0; i < 4; ++i) {
; #pragma unroll
;       for (int r = 0; r < 4; ++r) {
;         const int m = m0 + wm * 64 + i * 16 + g4 * 4 + r;
;         const int nb = n0 + wn * 64 + l15;
;         if (EPI == EPI_F32) {
;           float* cp = (float*)Cv + (size_t)m * ldc + nb;
; #pragma unroll
;           for (int j = 0; j < 4; ++j) if (nb + j * 16 < N) cp[j * 16] = acc[i][j][r];
;         } else {
;           u16* cp = (u16*)Cv + (size_t)m * ldc + nb;
; #pragma unroll
;           for (int j = 0; j < 4; ++j) {
;             float v = acc[i][j][r];
;             if (EPI == EPI_RELU2) { v = fmaxf(v, 0.f); v = v * v; }
;             if (nb + j * 16 < N) cp[j * 16] = f2bf(v);
;           }
	global_store_short_d16_hi v[80:81], v64, off
	v_bfe_u32 v64, v60, 16, 1
	v_max_f32_e32 v56, 0, v56
	v_add3_u32 v60, v60, v64, s96
	v_mul_f32_e32 v56, v56, v56
	v_max_f32_e32 v52, v52, v52
	global_store_short_d16_hi v[80:81], v60, off offset:32
	v_bfe_u32 v60, v56, 16, 1
	v_max_f32_e32 v52, 0, v52
	v_add3_u32 v56, v56, v60, s96
	v_mul_f32_e32 v52, v52, v52
	global_store_short_d16_hi v[80:81], v56, off offset:64
	v_bfe_u32 v56, v52, 16, 1
	v_add3_u32 v52, v52, v56, s96
	global_store_short_d16_hi v[80:81], v52, off offset:96
	v_max_f32_e32 v52, v65, v65
	v_or_b32_e32 v80, 1, v78
	v_max_f32_e32 v52, 0, v52
	v_ashrrev_i32_e32 v81, 31, v80
	v_mul_f32_e32 v52, v52, v52
	v_lshlrev_b64 v[80:81], 13, v[80:81]
	v_bfe_u32 v56, v52, 16, 1
	v_lshl_add_u64 v[80:81], v[76:77], 0, v[80:81]
	v_add3_u32 v52, v52, v56, s96
	global_store_short_d16_hi v[80:81], v52, off
	v_max_f32_e32 v52, v61, v61
	v_max_f32_e32 v52, 0, v52
	v_mul_f32_e32 v52, v52, v52
	v_bfe_u32 v56, v52, 16, 1
	v_add3_u32 v52, v52, v56, s96
	global_store_short_d16_hi v[80:81], v52, off offset:32
	v_max_f32_e32 v52, v57, v57
	v_max_f32_e32 v52, 0, v52
	v_mul_f32_e32 v52, v52, v52
	v_bfe_u32 v56, v52, 16, 1
	v_add3_u32 v52, v52, v56, s96
	global_store_short_d16_hi v[80:81], v52, off offset:64
	v_max_f32_e32 v52, v53, v53
	v_max_f32_e32 v52, 0, v52
	v_mul_f32_e32 v52, v52, v52
	v_bfe_u32 v53, v52, 16, 1
	v_add3_u32 v52, v52, v53, s96
	v_max_f32_e32 v56, v66, v66
	global_store_short_d16_hi v[80:81], v52, off offset:96
	v_or_b32_e32 v52, 2, v78
	v_max_f32_e32 v56, 0, v56
	v_ashrrev_i32_e32 v53, 31, v52
	v_mul_f32_e32 v56, v56, v56
	v_lshlrev_b64 v[52:53], 13, v[52:53]
	v_bfe_u32 v57, v56, 16, 1
	v_lshl_add_u64 v[52:53], v[76:77], 0, v[52:53]
	v_add3_u32 v56, v56, v57, s96
	global_store_short_d16_hi v[52:53], v56, off
	v_max_f32_e32 v56, v62, v62
	v_max_f32_e32 v56, 0, v56
	v_mul_f32_e32 v56, v56, v56
	v_bfe_u32 v57, v56, 16, 1
	v_add3_u32 v56, v56, v57, s96
	global_store_short_d16_hi v[52:53], v56, off offset:32
	v_max_f32_e32 v56, v58, v58
	v_max_f32_e32 v56, 0, v56
	v_mul_f32_e32 v56, v56, v56
	v_max_f32_e32 v54, v54, v54
	v_bfe_u32 v57, v56, 16, 1
	v_max_f32_e32 v54, 0, v54
	v_add3_u32 v56, v56, v57, s96
	v_mul_f32_e32 v54, v54, v54
	global_store_short_d16_hi v[52:53], v56, off offset:64
	v_bfe_u32 v56, v54, 16, 1
	v_add3_u32 v54, v54, v56, s96
	global_store_short_d16_hi v[52:53], v54, off offset:96
	v_max_f32_e32 v54, v67, v67
	v_or_b32_e32 v52, 3, v78
	v_max_f32_e32 v54, 0, v54
	v_ashrrev_i32_e32 v53, 31, v52
	v_mul_f32_e32 v54, v54, v54
	v_lshlrev_b64 v[52:53], 13, v[52:53]
	v_bfe_u32 v56, v54, 16, 1
	v_lshl_add_u64 v[52:53], v[76:77], 0, v[52:53]
	v_add3_u32 v54, v54, v56, s96
	global_store_short_d16_hi v[52:53], v54, off
	v_max_f32_e32 v54, v63, v63
	v_max_f32_e32 v54, 0, v54
	v_mul_f32_e32 v54, v54, v54
	v_bfe_u32 v56, v54, 16, 1
	v_add3_u32 v54, v54, v56, s96
	global_store_short_d16_hi v[52:53], v54, off offset:32
	v_max_f32_e32 v54, v59, v59
	v_max_f32_e32 v54, 0, v54
	v_mul_f32_e32 v54, v54, v54
	v_bfe_u32 v56, v54, 16, 1
	v_add3_u32 v54, v54, v56, s96
	global_store_short_d16_hi v[52:53], v54, off offset:64
	v_max_f32_e32 v54, v55, v55
	v_max_f32_e32 v54, 0, v54
	v_mul_f32_e32 v54, v54, v54
	v_bfe_u32 v55, v54, 16, 1
	v_add3_u32 v54, v54, v55, s96
	global_store_short_d16_hi v[52:53], v54, off offset:96
	v_max_f32_e32 v48, v48, v48
	v_or_b32_e32 v52, 16, v78
	v_max_f32_e32 v48, 0, v48
	v_ashrrev_i32_e32 v53, 31, v52
	v_mul_f32_e32 v48, v48, v48
	v_max_f32_e32 v44, v44, v44
	v_lshlrev_b64 v[52:53], 13, v[52:53]
	v_bfe_u32 v54, v48, 16, 1
	v_max_f32_e32 v44, 0, v44
	v_lshl_add_u64 v[52:53], v[76:77], 0, v[52:53]
	v_add3_u32 v48, v48, v54, s96
	v_mul_f32_e32 v44, v44, v44
	v_max_f32_e32 v40, v40, v40
	global_store_short_d16_hi v[52:53], v48, off
	v_bfe_u32 v48, v44, 16, 1
	v_max_f32_e32 v40, 0, v40
	v_add3_u32 v44, v44, v48, s96
	v_mul_f32_e32 v40, v40, v40
	v_max_f32_e32 v36, v36, v36
	global_store_short_d16_hi v[52:53], v44, off offset:32
	v_bfe_u32 v44, v40, 16, 1
	v_max_f32_e32 v36, 0, v36
	v_add3_u32 v40, v40, v44, s96
	v_mul_f32_e32 v36, v36, v36
	global_store_short_d16_hi v[52:53], v40, off offset:64
	v_bfe_u32 v40, v36, 16, 1
	v_add3_u32 v36, v36, v40, s96
	global_store_short_d16_hi v[52:53], v36, off offset:96
	v_max_f32_e32 v36, v49, v49
	v_or_b32_e32 v52, 17, v78
	v_max_f32_e32 v36, 0, v36
	v_ashrrev_i32_e32 v53, 31, v52
	v_mul_f32_e32 v36, v36, v36
	v_lshlrev_b64 v[52:53], 13, v[52:53]
	v_bfe_u32 v40, v36, 16, 1
	v_lshl_add_u64 v[52:53], v[76:77], 0, v[52:53]
	v_add3_u32 v36, v36, v40, s96
	global_store_short_d16_hi v[52:53], v36, off
	v_max_f32_e32 v36, v45, v45
	v_max_f32_e32 v36, 0, v36
	v_mul_f32_e32 v36, v36, v36
	v_bfe_u32 v40, v36, 16, 1
	v_add3_u32 v36, v36, v40, s96
	global_store_short_d16_hi v[52:53], v36, off offset:32
	v_max_f32_e32 v36, v41, v41
	v_max_f32_e32 v36, 0, v36
	v_mul_f32_e32 v36, v36, v36
	v_bfe_u32 v40, v36, 16, 1
	v_add3_u32 v36, v36, v40, s96
	global_store_short_d16_hi v[52:53], v36, off offset:64
	v_max_f32_e32 v36, v37, v37
	v_max_f32_e32 v36, 0, v36
	v_mul_f32_e32 v36, v36, v36
	v_bfe_u32 v37, v36, 16, 1
	v_add3_u32 v36, v36, v37, s96
	v_max_f32_e32 v40, v50, v50
	global_store_short_d16_hi v[52:53], v36, off offset:96
	v_or_b32_e32 v36, 18, v78
	v_max_f32_e32 v40, 0, v40
	v_ashrrev_i32_e32 v37, 31, v36
	v_mul_f32_e32 v40, v40, v40
	v_lshlrev_b64 v[36:37], 13, v[36:37]
	v_bfe_u32 v41, v40, 16, 1
	v_lshl_add_u64 v[36:37], v[76:77], 0, v[36:37]
	v_add3_u32 v40, v40, v41, s96
	global_store_short_d16_hi v[36:37], v40, off
	v_max_f32_e32 v40, v46, v46
	v_max_f32_e32 v40, 0, v40
	v_mul_f32_e32 v40, v40, v40
	v_bfe_u32 v41, v40, 16, 1
; template <int EPI>
; __device__ void gemm_phase(const u16* __restrict__ A, const u16* __restrict__ Bt, void* __restrict__ Cv,
;                            int N, int K, int ldc, unsigned char* ldsraw, int G) {
;     ...
;     for (int i = 0; i < 4; ++i) {
; #pragma unroll
;       for (int r = 0; r < 4; ++r) {
;         const int m = m0 + wm * 64 + i * 16 + g4 * 4 + r;
;         const int nb = n0 + wn * 64 + l15;
;         if (EPI == EPI_F32) {
;           float* cp = (float*)Cv + (size_t)m * ldc + nb;
; #pragma unroll
;           for (int j = 0; j < 4; ++j) if (nb + j * 16 < N) cp[j * 16] = acc[i][j][r];
;         } else {
;           u16* cp = (u16*)Cv + (size_t)m * ldc + nb;
; #pragma unroll
;           for (int j = 0; j < 4; ++j) {
;             float v = acc[i][j][r];
;             if (EPI == EPI_RELU2) { v = fmaxf(v, 0.f); v = v * v; }
;             if (nb + j * 16 < N) cp[j * 16] = f2bf(v);
;           }
	v_add3_u32 v40, v40, v41, s96
	global_store_short_d16_hi v[36:37], v40, off offset:32
	v_max_f32_e32 v40, v42, v42
	v_max_f32_e32 v40, 0, v40
	v_mul_f32_e32 v40, v40, v40
	v_max_f32_e32 v38, v38, v38
	v_bfe_u32 v41, v40, 16, 1
	v_max_f32_e32 v38, 0, v38
	v_add3_u32 v40, v40, v41, s96
	v_mul_f32_e32 v38, v38, v38
	global_store_short_d16_hi v[36:37], v40, off offset:64
	v_bfe_u32 v40, v38, 16, 1
	v_add3_u32 v38, v38, v40, s96
	global_store_short_d16_hi v[36:37], v38, off offset:96
	v_max_f32_e32 v38, v51, v51
	v_or_b32_e32 v36, 19, v78
	v_max_f32_e32 v38, 0, v38
	v_ashrrev_i32_e32 v37, 31, v36
	v_mul_f32_e32 v38, v38, v38
	v_lshlrev_b64 v[36:37], 13, v[36:37]
	v_bfe_u32 v40, v38, 16, 1
	v_lshl_add_u64 v[36:37], v[76:77], 0, v[36:37]
	v_add3_u32 v38, v38, v40, s96
	global_store_short_d16_hi v[36:37], v38, off
	v_max_f32_e32 v38, v47, v47
	v_max_f32_e32 v38, 0, v38
	v_mul_f32_e32 v38, v38, v38
	v_bfe_u32 v40, v38, 16, 1
	v_add3_u32 v38, v38, v40, s96
	global_store_short_d16_hi v[36:37], v38, off offset:32
	v_max_f32_e32 v38, v43, v43
	v_max_f32_e32 v38, 0, v38
	v_mul_f32_e32 v38, v38, v38
	v_bfe_u32 v40, v38, 16, 1
	v_add3_u32 v38, v38, v40, s96
	global_store_short_d16_hi v[36:37], v38, off offset:64
	v_max_f32_e32 v38, v39, v39
	v_max_f32_e32 v38, 0, v38
	v_mul_f32_e32 v38, v38, v38
	v_bfe_u32 v39, v38, 16, 1
	v_add3_u32 v38, v38, v39, s96
	global_store_short_d16_hi v[36:37], v38, off offset:96
	v_max_f32_e32 v32, v32, v32
	v_or_b32_e32 v36, 32, v78
	v_max_f32_e32 v32, 0, v32
	v_ashrrev_i32_e32 v37, 31, v36
	v_mul_f32_e32 v32, v32, v32
	v_max_f32_e32 v28, v28, v28
	v_lshlrev_b64 v[36:37], 13, v[36:37]
	v_bfe_u32 v38, v32, 16, 1
	v_max_f32_e32 v28, 0, v28
	v_lshl_add_u64 v[36:37], v[76:77], 0, v[36:37]
	v_add3_u32 v32, v32, v38, s96
	v_mul_f32_e32 v28, v28, v28
	v_max_f32_e32 v24, v24, v24
	global_store_short_d16_hi v[36:37], v32, off
	v_bfe_u32 v32, v28, 16, 1
	v_max_f32_e32 v24, 0, v24
	v_add3_u32 v28, v28, v32, s96
	v_mul_f32_e32 v24, v24, v24
	v_max_f32_e32 v20, v20, v20
	global_store_short_d16_hi v[36:37], v28, off offset:32
	v_bfe_u32 v28, v24, 16, 1
	v_max_f32_e32 v20, 0, v20
	v_add3_u32 v24, v24, v28, s96
	v_mul_f32_e32 v20, v20, v20
	global_store_short_d16_hi v[36:37], v24, off offset:64
	v_bfe_u32 v24, v20, 16, 1
	v_add3_u32 v20, v20, v24, s96
	global_store_short_d16_hi v[36:37], v20, off offset:96
	v_max_f32_e32 v20, v33, v33
	v_or_b32_e32 v36, 33, v78
	v_max_f32_e32 v20, 0, v20
	v_ashrrev_i32_e32 v37, 31, v36
	v_mul_f32_e32 v20, v20, v20
	v_lshlrev_b64 v[36:37], 13, v[36:37]
	v_bfe_u32 v24, v20, 16, 1
	v_lshl_add_u64 v[36:37], v[76:77], 0, v[36:37]
	v_add3_u32 v20, v20, v24, s96
	global_store_short_d16_hi v[36:37], v20, off
	v_max_f32_e32 v20, v29, v29
	v_max_f32_e32 v20, 0, v20
	v_mul_f32_e32 v20, v20, v20
	v_bfe_u32 v24, v20, 16, 1
	v_add3_u32 v20, v20, v24, s96
	global_store_short_d16_hi v[36:37], v20, off offset:32
	v_max_f32_e32 v20, v25, v25
	v_max_f32_e32 v20, 0, v20
	v_mul_f32_e32 v20, v20, v20
	v_bfe_u32 v24, v20, 16, 1
	v_add3_u32 v20, v20, v24, s96
	global_store_short_d16_hi v[36:37], v20, off offset:64
	v_max_f32_e32 v20, v21, v21
	v_max_f32_e32 v20, 0, v20
	v_mul_f32_e32 v20, v20, v20
	v_bfe_u32 v21, v20, 16, 1
	v_add3_u32 v20, v20, v21, s96
	v_max_f32_e32 v24, v34, v34
	global_store_short_d16_hi v[36:37], v20, off offset:96
	v_or_b32_e32 v20, 34, v78
	v_max_f32_e32 v24, 0, v24
	v_ashrrev_i32_e32 v21, 31, v20
	v_mul_f32_e32 v24, v24, v24
	v_lshlrev_b64 v[20:21], 13, v[20:21]
	v_bfe_u32 v25, v24, 16, 1
	v_lshl_add_u64 v[20:21], v[76:77], 0, v[20:21]
	v_add3_u32 v24, v24, v25, s96
	global_store_short_d16_hi v[20:21], v24, off
	v_max_f32_e32 v24, v30, v30
	v_max_f32_e32 v24, 0, v24
	v_mul_f32_e32 v24, v24, v24
	v_bfe_u32 v25, v24, 16, 1
	v_add3_u32 v24, v24, v25, s96
	global_store_short_d16_hi v[20:21], v24, off offset:32
	v_max_f32_e32 v24, v26, v26
	v_max_f32_e32 v24, 0, v24
	v_mul_f32_e32 v24, v24, v24
	v_max_f32_e32 v22, v22, v22
	v_bfe_u32 v25, v24, 16, 1
	v_max_f32_e32 v22, 0, v22
	v_add3_u32 v24, v24, v25, s96
	v_mul_f32_e32 v22, v22, v22
	global_store_short_d16_hi v[20:21], v24, off offset:64
	v_bfe_u32 v24, v22, 16, 1
	v_add3_u32 v22, v22, v24, s96
	global_store_short_d16_hi v[20:21], v22, off offset:96
	v_max_f32_e32 v22, v35, v35
	v_or_b32_e32 v20, 35, v78
	v_max_f32_e32 v22, 0, v22
	v_ashrrev_i32_e32 v21, 31, v20
	v_mul_f32_e32 v22, v22, v22
; template <int EPI>
; __device__ void gemm_phase(const u16* __restrict__ A, const u16* __restrict__ Bt, void* __restrict__ Cv,
;                            int N, int K, int ldc, unsigned char* ldsraw, int G) {
;     ...
;     for (int i = 0; i < 4; ++i) {
; #pragma unroll
;       for (int r = 0; r < 4; ++r) {
;         const int m = m0 + wm * 64 + i * 16 + g4 * 4 + r;
;         const int nb = n0 + wn * 64 + l15;
;         if (EPI == EPI_F32) {
;           float* cp = (float*)Cv + (size_t)m * ldc + nb;
; #pragma unroll
;           for (int j = 0; j < 4; ++j) if (nb + j * 16 < N) cp[j * 16] = acc[i][j][r];
;         } else {
;           u16* cp = (u16*)Cv + (size_t)m * ldc + nb;
; #pragma unroll
;           for (int j = 0; j < 4; ++j) {
;             float v = acc[i][j][r];
;             if (EPI == EPI_RELU2) { v = fmaxf(v, 0.f); v = v * v; }
;             if (nb + j * 16 < N) cp[j * 16] = f2bf(v);
;           }
;         }
;       }
;       __builtin_amdgcn_sched_barrier(0);
;     }
;   }
	v_lshlrev_b64 v[20:21], 13, v[20:21]
	v_bfe_u32 v24, v22, 16, 1
	v_lshl_add_u64 v[20:21], v[76:77], 0, v[20:21]
	v_add3_u32 v22, v22, v24, s96
	global_store_short_d16_hi v[20:21], v22, off
	v_max_f32_e32 v22, v31, v31
	v_max_f32_e32 v22, 0, v22
	v_mul_f32_e32 v22, v22, v22
	v_bfe_u32 v24, v22, 16, 1
	v_add3_u32 v22, v22, v24, s96
	global_store_short_d16_hi v[20:21], v22, off offset:32
	v_max_f32_e32 v22, v27, v27
	v_max_f32_e32 v22, 0, v22
	v_mul_f32_e32 v22, v22, v22
	v_bfe_u32 v24, v22, 16, 1
	v_add3_u32 v22, v22, v24, s96
	global_store_short_d16_hi v[20:21], v22, off offset:64
	v_max_f32_e32 v22, v23, v23
	v_max_f32_e32 v22, 0, v22
	v_mul_f32_e32 v22, v22, v22
	v_bfe_u32 v23, v22, 16, 1
	v_add3_u32 v22, v22, v23, s96
	global_store_short_d16_hi v[20:21], v22, off offset:96
	v_max_f32_e32 v16, v16, v16
	v_or_b32_e32 v20, 48, v78
	v_max_f32_e32 v16, 0, v16
	v_ashrrev_i32_e32 v21, 31, v20
	v_mul_f32_e32 v16, v16, v16
	v_max_f32_e32 v12, v12, v12
	v_lshlrev_b64 v[20:21], 13, v[20:21]
	v_bfe_u32 v22, v16, 16, 1
	v_max_f32_e32 v12, 0, v12
	v_lshl_add_u64 v[20:21], v[76:77], 0, v[20:21]
	v_add3_u32 v16, v16, v22, s96
	v_mul_f32_e32 v12, v12, v12
	v_max_f32_e32 v8, v8, v8
	global_store_short_d16_hi v[20:21], v16, off
	v_bfe_u32 v16, v12, 16, 1
	v_max_f32_e32 v8, 0, v8
	v_add3_u32 v12, v12, v16, s96
	v_mul_f32_e32 v8, v8, v8
	v_max_f32_e32 v2, v2, v2
	global_store_short_d16_hi v[20:21], v12, off offset:32
	v_bfe_u32 v12, v8, 16, 1
	v_max_f32_e32 v2, 0, v2
	v_add3_u32 v8, v8, v12, s96
	v_mul_f32_e32 v2, v2, v2
	global_store_short_d16_hi v[20:21], v8, off offset:64
	v_bfe_u32 v8, v2, 16, 1
	v_add3_u32 v2, v2, v8, s96
	global_store_short_d16_hi v[20:21], v2, off offset:96
	v_max_f32_e32 v2, v17, v17
	v_or_b32_e32 v20, 49, v78
	v_max_f32_e32 v2, 0, v2
	v_ashrrev_i32_e32 v21, 31, v20
	v_mul_f32_e32 v2, v2, v2
	v_lshlrev_b64 v[20:21], 13, v[20:21]
	v_bfe_u32 v8, v2, 16, 1
	v_lshl_add_u64 v[20:21], v[76:77], 0, v[20:21]
	v_add3_u32 v2, v2, v8, s96
	global_store_short_d16_hi v[20:21], v2, off
	v_max_f32_e32 v2, v13, v13
	v_max_f32_e32 v2, 0, v2
	v_mul_f32_e32 v2, v2, v2
	v_bfe_u32 v8, v2, 16, 1
	v_add3_u32 v2, v2, v8, s96
	global_store_short_d16_hi v[20:21], v2, off offset:32
	v_max_f32_e32 v2, v9, v9
	v_max_f32_e32 v2, 0, v2
	v_mul_f32_e32 v2, v2, v2
	v_bfe_u32 v8, v2, 16, 1
	v_add3_u32 v2, v2, v8, s96
	global_store_short_d16_hi v[20:21], v2, off offset:64
	v_max_f32_e32 v2, v3, v3
	v_max_f32_e32 v2, 0, v2
	v_mul_f32_e32 v2, v2, v2
	v_bfe_u32 v3, v2, 16, 1
	v_add3_u32 v2, v2, v3, s96
	v_max_f32_e32 v8, v18, v18
	global_store_short_d16_hi v[20:21], v2, off offset:96
	v_or_b32_e32 v2, 50, v78
	v_max_f32_e32 v8, 0, v8
	v_ashrrev_i32_e32 v3, 31, v2
	v_mul_f32_e32 v8, v8, v8
	v_lshlrev_b64 v[2:3], 13, v[2:3]
	v_bfe_u32 v9, v8, 16, 1
	v_lshl_add_u64 v[2:3], v[76:77], 0, v[2:3]
	v_add3_u32 v8, v8, v9, s96
	global_store_short_d16_hi v[2:3], v8, off
	v_max_f32_e32 v8, v14, v14
	v_max_f32_e32 v8, 0, v8
	v_mul_f32_e32 v8, v8, v8
	v_bfe_u32 v9, v8, 16, 1
	v_add3_u32 v8, v8, v9, s96
	global_store_short_d16_hi v[2:3], v8, off offset:32
	v_max_f32_e32 v8, v10, v10
	v_max_f32_e32 v8, 0, v8
	v_mul_f32_e32 v8, v8, v8
	v_max_f32_e32 v4, v4, v4
	v_bfe_u32 v9, v8, 16, 1
	v_max_f32_e32 v4, 0, v4
	v_add3_u32 v8, v8, v9, s96
	v_mul_f32_e32 v4, v4, v4
	global_store_short_d16_hi v[2:3], v8, off offset:64
	v_bfe_u32 v8, v4, 16, 1
	v_add3_u32 v4, v4, v8, s96
	global_store_short_d16_hi v[2:3], v4, off offset:96
	v_max_f32_e32 v4, v19, v19
	v_or_b32_e32 v2, 51, v78
	v_max_f32_e32 v4, 0, v4
	v_ashrrev_i32_e32 v3, 31, v2
	v_mul_f32_e32 v4, v4, v4
	v_lshlrev_b64 v[2:3], 13, v[2:3]
	v_bfe_u32 v8, v4, 16, 1
	v_lshl_add_u64 v[2:3], v[76:77], 0, v[2:3]
	v_add3_u32 v4, v4, v8, s96
	global_store_short_d16_hi v[2:3], v4, off
	v_max_f32_e32 v4, v15, v15
	v_max_f32_e32 v4, 0, v4
	v_mul_f32_e32 v4, v4, v4
	v_bfe_u32 v8, v4, 16, 1
	v_add3_u32 v4, v4, v8, s96
	global_store_short_d16_hi v[2:3], v4, off offset:32
	v_max_f32_e32 v4, v11, v11
	v_max_f32_e32 v4, 0, v4
	v_mul_f32_e32 v4, v4, v4
	v_bfe_u32 v8, v4, 16, 1
	v_add3_u32 v4, v4, v8, s96
	global_store_short_d16_hi v[2:3], v4, off offset:64
	v_max_f32_e32 v4, v5, v5
	v_max_f32_e32 v4, 0, v4
	v_mul_f32_e32 v4, v4, v4
	v_bfe_u32 v5, v4, 16, 1
	v_add3_u32 v4, v4, v5, s96
	global_store_short_d16_hi v[2:3], v4, off offset:96
	s_add_i32 s0, s0, s33
	s_cmpk_gt_i32 s0, 0x7ff
	s_cbranch_scc0 .LBB0_154

; __device__ __forceinline__ void lds_barrier() { asm volatile("s_waitcnt lgkmcnt(0)\n\ts_barrier" ::: "memory"); }
; template <int EPI>
; __device__ void gemm_phase(const u16* __restrict__ A, const u16* __restrict__ Bt, void* __restrict__ Cv,
;                            int N, int K, int ldc, unsigned char* ldsraw, int G) {
;     ...
;     for (int kt = 0; kt < nk; ++kt) {
;       asm volatile("s_waitcnt vmcnt(6)" ::: "memory");
;       lds_barrier();
;       const int st2 = (st >= 1) ? st - 1 : 2;
;       GLDS(st2, kt + 2);
;       const u16* Asx = As + st * STG;
;       const u16* Bsx = Asx + GBM * GLD;
; #pragma unroll
;       for (int ks = 0; ks < 2; ++ks) {
;         const int fsw = ((ks * 4 + g4) ^ fx) * 8;
;         bf16x8 bfr[4];
; #pragma unroll
;         for (int jx = 0; jx < 4; ++jx) bfr[jx] = *(const bf16x8*)(Bsx + (wn * 64 + jx * 16 + l15) * GLD + fsw);
; #pragma unroll
;         for (int ix = 0; ix < 4; ++ix) {
;           const bf16x8 af = *(const bf16x8*)(Asx + (wm * 64 + ix * 16 + l15) * GLD + fsw);
; #pragma unroll
;           for (int jx = 0; jx < 4; ++jx)
;             acc[ix][jx] = __builtin_amdgcn_mfma_f32_16x16x32_bf16(af, bfr[jx], acc[ix][jx], 0, 0, 0);
;         }
;       }
;       st = (st == 2) ? 0 : st + 1;
;     }
;     ...
;     for (int i = 0; i < 4; ++i) {
; #pragma unroll
;       for (int r = 0; r < 4; ++r) {
;         const int m = m0 + wm * 64 + i * 16 + g4 * 4 + r;
;         const int nb = n0 + wn * 64 + l15;
;         if (EPI == EPI_F32) {
;           float* cp = (float*)Cv + (size_t)m * ldc + nb;
; #pragma unroll
;           for (int j = 0; j < 4; ++j) if (nb + j * 16 < N) cp[j * 16] = acc[i][j][r];
;         } else {
;           u16* cp = (u16*)Cv + (size_t)m * ldc + nb;
; #pragma unroll
;           for (int j = 0; j < 4; ++j) {
;             float v = acc[i][j][r];
;             if (EPI == EPI_RELU2) { v = fmaxf(v, 0.f); v = v * v; }
;             if (nb + j * 16 < N) cp[j * 16] = f2bf(v);
.LBB0_176:
	s_mul_i32 s8, s5, 0xc000
	s_min_u32 s7, s6, 13
	s_add_i32 s9, s8, 0xffff4000
	s_cmp_gt_i32 s5, 0
	s_waitcnt vmcnt(6)
	s_cselect_b32 s9, s9, 0x18000
	s_lshl_b32 s98, s7, 7
	s_add_i32 s7, s8, 0x100
	s_add_i32 s8, s9, s4
	s_add_i32 s9, s8, 0x2000
	s_add_i32 s11, s8, 0x4000
	s_add_i32 s12, s8, 0x6000
	s_add_i32 s13, s8, 0x8000
	s_add_i32 s14, s8, 0xa000
	v_lshl_add_u64 v[236:237], v[76:77], 0, s[98:99]
	v_lshl_add_u64 v[238:239], v[80:81], 0, s[98:99]
	v_lshl_add_u64 v[236:237], v[236:237], 0, s[42:43]
	v_lshl_add_u64 v[240:241], v[82:83], 0, s[98:99]
	v_lshl_add_u64 v[238:239], v[238:239], 0, s[42:43]
	v_lshl_add_u64 v[242:243], v[84:85], 0, s[98:99]
	v_lshl_add_u64 v[240:241], v[240:241], 0, s[42:43]
	v_lshl_add_u64 v[244:245], v[78:79], 0, s[98:99]
	v_lshl_add_u64 v[242:243], v[242:243], 0, s[42:43]
	v_lshl_add_u64 v[246:247], v[86:87], 0, s[98:99]
	v_lshl_add_u64 v[244:245], v[244:245], 0, s[42:43]
	v_lshl_add_u64 v[246:247], v[246:247], 0, s[42:43]
	v_lshl_add_u32 v109, v104, 1, s7
	v_add3_u32 v130, v109, v105, v106
	v_add3_u32 v109, v109, v107, v106
	s_waitcnt lgkmcnt(0)
	s_barrier
	s_mov_b32 s15, m0
	ds_read_b128 v[110:113], v109
	ds_read_b128 v[114:117], v130 offset:32768
	ds_read_b128 v[118:121], v130 offset:34816
	ds_read_b128 v[122:125], v109 offset:2048
	ds_read_b128 v[126:129], v130 offset:36864
	ds_read_b128 v[130:133], v130 offset:38912
	s_waitcnt lgkmcnt(4)
	v_mfma_f32_16x16x32_bf16 v[64:67], v[110:113], v[114:117], v[64:67]
	s_waitcnt lgkmcnt(3)
	v_mfma_f32_16x16x32_bf16 v[60:63], v[110:113], v[118:121], v[60:63]
	s_waitcnt lgkmcnt(1)
	v_mfma_f32_16x16x32_bf16 v[56:59], v[110:113], v[126:129], v[56:59]
	s_waitcnt lgkmcnt(0)
	s_mov_b32 m0, s8
	v_mfma_f32_16x16x32_bf16 v[52:55], v[110:113], v[130:133], v[52:55]
	global_load_lds_dwordx4 v[236:237], off
	v_mfma_f32_16x16x32_bf16 v[48:51], v[122:125], v[114:117], v[48:51]
	v_mfma_f32_16x16x32_bf16 v[44:47], v[122:125], v[118:121], v[44:47]
	v_mfma_f32_16x16x32_bf16 v[40:43], v[122:125], v[126:129], v[40:43]
	v_mfma_f32_16x16x32_bf16 v[36:39], v[122:125], v[130:133], v[36:39]
	ds_read_b128 v[110:113], v109 offset:4096
	ds_read_b128 v[122:125], v109 offset:6144
	v_lshl_add_u32 v109, v108, 1, s7
	v_add3_u32 v134, v109, v105, v106
	v_add3_u32 v109, v109, v107, v106
	s_waitcnt lgkmcnt(1)
	s_mov_b32 m0, s9
	v_mfma_f32_16x16x32_bf16 v[32:35], v[110:113], v[114:117], v[32:35]
	global_load_lds_dwordx4 v[238:239], off
	s_add_i32 s7, s5, 1
	s_cmp_lg_u32 s5, 2
	s_cselect_b32 s5, s7, 0
	v_mfma_f32_16x16x32_bf16 v[28:31], v[110:113], v[118:121], v[28:31]
	s_add_i32 s6, s6, 1
	s_cmp_eq_u32 s6, 16
	v_mfma_f32_16x16x32_bf16 v[24:27], v[110:113], v[126:129], v[24:27]
	v_mfma_f32_16x16x32_bf16 v[20:23], v[110:113], v[130:133], v[20:23]
	ds_read_b128 v[110:113], v109
	s_waitcnt lgkmcnt(1)
	v_mfma_f32_16x16x32_bf16 v[16:19], v[122:125], v[114:117], v[16:19]
	s_mov_b32 m0, s11
	v_mfma_f32_16x16x32_bf16 v[12:15], v[122:125], v[118:121], v[12:15]
	global_load_lds_dwordx4 v[240:241], off
	v_mfma_f32_16x16x32_bf16 v[8:11], v[122:125], v[126:129], v[8:11]
	v_mfma_f32_16x16x32_bf16 v[2:5], v[122:125], v[130:133], v[2:5]
	ds_read_b128 v[114:117], v134 offset:32768
	ds_read_b128 v[118:121], v134 offset:34816
	ds_read_b128 v[122:125], v109 offset:2048
	ds_read_b128 v[126:129], v134 offset:36864
	ds_read_b128 v[130:133], v134 offset:38912
	s_waitcnt lgkmcnt(4)
	v_mfma_f32_16x16x32_bf16 v[64:67], v[110:113], v[114:117], v[64:67]
	s_waitcnt lgkmcnt(3)
	v_mfma_f32_16x16x32_bf16 v[60:63], v[110:113], v[118:121], v[60:63]
	s_waitcnt lgkmcnt(1)
	s_mov_b32 m0, s12
	v_mfma_f32_16x16x32_bf16 v[56:59], v[110:113], v[126:129], v[56:59]
	global_load_lds_dwordx4 v[242:243], off
	s_waitcnt lgkmcnt(0)
	v_mfma_f32_16x16x32_bf16 v[52:55], v[110:113], v[130:133], v[52:55]
	v_mfma_f32_16x16x32_bf16 v[48:51], v[122:125], v[114:117], v[48:51]
	v_mfma_f32_16x16x32_bf16 v[44:47], v[122:125], v[118:121], v[44:47]
	v_mfma_f32_16x16x32_bf16 v[40:43], v[122:125], v[126:129], v[40:43]
	s_mov_b32 m0, s13
	v_mfma_f32_16x16x32_bf16 v[36:39], v[122:125], v[130:133], v[36:39]
	global_load_lds_dwordx4 v[244:245], off
	ds_read_b128 v[110:113], v109 offset:4096
	ds_read_b128 v[122:125], v109 offset:6144
	s_waitcnt lgkmcnt(1)
	v_mfma_f32_16x16x32_bf16 v[32:35], v[110:113], v[114:117], v[32:35]
	v_mfma_f32_16x16x32_bf16 v[28:31], v[110:113], v[118:121], v[28:31]
	v_mfma_f32_16x16x32_bf16 v[24:27], v[110:113], v[126:129], v[24:27]
	v_mfma_f32_16x16x32_bf16 v[20:23], v[110:113], v[130:133], v[20:23]
	s_waitcnt lgkmcnt(0)
	s_mov_b32 m0, s14
	v_mfma_f32_16x16x32_bf16 v[16:19], v[122:125], v[114:117], v[16:19]
	global_load_lds_dwordx4 v[246:247], off
	s_mov_b32 m0, s15
	v_mfma_f32_16x16x32_bf16 v[12:15], v[122:125], v[118:121], v[12:15]
	v_mfma_f32_16x16x32_bf16 v[8:11], v[122:125], v[126:129], v[8:11]
	v_mfma_f32_16x16x32_bf16 v[2:5], v[122:125], v[130:133], v[2:5]
	s_cbranch_scc0 .LBB0_176
	s_setprio 0
	s_waitcnt vmcnt(0)
	v_add_u32_e32 v78, s0, v0
	v_or_b32_e32 v82, s1, v75
	s_waitcnt lgkmcnt(0)
	s_barrier
	v_ashrrev_i32_e32 v83, 31, v82
	v_ashrrev_i32_e32 v79, 31, v78
	v_lshl_add_u64 v[76:77], v[82:83], 1, s[76:77]
	v_lshlrev_b64 v[80:81], 11, v[78:79]
	s_movk_i32 s0, 0x400
	v_lshl_add_u64 v[80:81], v[76:77], 0, v[80:81]
	v_cmp_gt_i32_e32 vcc, s0, v82
	s_and_saveexec_b64 s[0:1], vcc
	s_cbranch_execz .LBB0_179
	v_bfe_u32 v79, v64, 16, 1
	v_add3_u32 v64, v64, v79, s96
	global_store_short_d16_hi v[80:81], v64, off

; __device__ __forceinline__ void lds_barrier() { asm volatile("s_waitcnt lgkmcnt(0)\n\ts_barrier" ::: "memory"); }
; template <int EPI>
; __device__ void gemm_phase(const u16* __restrict__ A, const u16* __restrict__ Bt, void* __restrict__ Cv,
;                            int N, int K, int ldc, unsigned char* ldsraw, int G) {
;     ...
;     for (int kt = 0; kt < nk; ++kt) {
;       asm volatile("s_waitcnt vmcnt(6)" ::: "memory");
;       lds_barrier();
;       const int st2 = (st >= 1) ? st - 1 : 2;
;       GLDS(st2, kt + 2);
;       const u16* Asx = As + st * STG;
;       const u16* Bsx = Asx + GBM * GLD;
; #pragma unroll
;       for (int ks = 0; ks < 2; ++ks) {
;         const int fsw = ((ks * 4 + g4) ^ fx) * 8;
;         bf16x8 bfr[4];
; #pragma unroll
;         for (int jx = 0; jx < 4; ++jx) bfr[jx] = *(const bf16x8*)(Bsx + (wn * 64 + jx * 16 + l15) * GLD + fsw);
; #pragma unroll
;         for (int ix = 0; ix < 4; ++ix) {
;           const bf16x8 af = *(const bf16x8*)(Asx + (wm * 64 + ix * 16 + l15) * GLD + fsw);
; #pragma unroll
;           for (int jx = 0; jx < 4; ++jx)
;             acc[ix][jx] = __builtin_amdgcn_mfma_f32_16x16x32_bf16(af, bfr[jx], acc[ix][jx], 0, 0, 0);
;         }
;       }
;       st = (st == 2) ? 0 : st + 1;
;     }
;     ...
;     for (int i = 0; i < 4; ++i) {
; #pragma unroll
;       for (int r = 0; r < 4; ++r) {
;         const int m = m0 + wm * 64 + i * 16 + g4 * 4 + r;
;         const int nb = n0 + wn * 64 + l15;
;         if (EPI == EPI_F32) {
;           float* cp = (float*)Cv + (size_t)m * ldc + nb;
; #pragma unroll
;           for (int j = 0; j < 4; ++j) if (nb + j * 16 < N) cp[j * 16] = acc[i][j][r];
;         } else {
;           u16* cp = (u16*)Cv + (size_t)m * ldc + nb;
; #pragma unroll
;           for (int j = 0; j < 4; ++j) {
;             float v = acc[i][j][r];
;             if (EPI == EPI_RELU2) { v = fmaxf(v, 0.f); v = v * v; }
;             if (nb + j * 16 < N) cp[j * 16] = f2bf(v);
.LBB0_830:
	s_mul_i32 s7, s4, 0xc000
	s_min_u32 s6, s5, 13
	s_add_i32 s8, s7, 0xffff4000
	s_cmp_gt_i32 s4, 0
	s_waitcnt vmcnt(6)
	s_cselect_b32 s8, s8, 0x18000
	s_lshl_b32 s98, s6, 7
	s_add_i32 s6, s7, 0x100
	s_add_i32 s7, s8, s3
	s_add_i32 s8, s7, 0x2000
	s_add_i32 s9, s7, 0x4000
	s_add_i32 s10, s7, 0x6000
	s_add_i32 s11, s7, 0x8000
	s_add_i32 s12, s7, 0xa000
	v_lshl_add_u64 v[236:237], v[76:77], 0, s[98:99]
	v_lshl_add_u64 v[238:239], v[80:81], 0, s[98:99]
	v_lshl_add_u64 v[236:237], v[236:237], 0, s[42:43]
	v_lshl_add_u64 v[240:241], v[82:83], 0, s[98:99]
	v_lshl_add_u64 v[238:239], v[238:239], 0, s[42:43]
	v_lshl_add_u64 v[242:243], v[84:85], 0, s[98:99]
	v_lshl_add_u64 v[240:241], v[240:241], 0, s[42:43]
	v_lshl_add_u64 v[244:245], v[78:79], 0, s[98:99]
	v_lshl_add_u64 v[242:243], v[242:243], 0, s[42:43]
	v_lshl_add_u64 v[246:247], v[86:87], 0, s[98:99]
	v_lshl_add_u64 v[244:245], v[244:245], 0, s[42:43]
	v_lshl_add_u64 v[246:247], v[246:247], 0, s[42:43]
	v_lshl_add_u32 v109, v104, 1, s6
	v_add3_u32 v130, v109, v105, v106
	v_add3_u32 v109, v109, v107, v106
	s_waitcnt lgkmcnt(0)
	s_barrier
	s_mov_b32 s13, m0
	ds_read_b128 v[110:113], v109
	ds_read_b128 v[114:117], v130 offset:32768
	ds_read_b128 v[118:121], v130 offset:34816
	ds_read_b128 v[122:125], v109 offset:2048
	ds_read_b128 v[126:129], v130 offset:36864
	ds_read_b128 v[130:133], v130 offset:38912
	s_waitcnt lgkmcnt(4)
	v_mfma_f32_16x16x32_bf16 v[64:67], v[110:113], v[114:117], v[64:67]
	s_waitcnt lgkmcnt(3)
	v_mfma_f32_16x16x32_bf16 v[60:63], v[110:113], v[118:121], v[60:63]
	s_waitcnt lgkmcnt(1)
	v_mfma_f32_16x16x32_bf16 v[56:59], v[110:113], v[126:129], v[56:59]
	s_waitcnt lgkmcnt(0)
	s_mov_b32 m0, s7
	v_mfma_f32_16x16x32_bf16 v[52:55], v[110:113], v[130:133], v[52:55]
	global_load_lds_dwordx4 v[236:237], off
	v_mfma_f32_16x16x32_bf16 v[48:51], v[122:125], v[114:117], v[48:51]
	v_mfma_f32_16x16x32_bf16 v[44:47], v[122:125], v[118:121], v[44:47]
	v_mfma_f32_16x16x32_bf16 v[40:43], v[122:125], v[126:129], v[40:43]
	v_mfma_f32_16x16x32_bf16 v[36:39], v[122:125], v[130:133], v[36:39]
	ds_read_b128 v[110:113], v109 offset:4096
	ds_read_b128 v[122:125], v109 offset:6144
	v_lshl_add_u32 v109, v108, 1, s6
	v_add3_u32 v134, v109, v105, v106
	v_add3_u32 v109, v109, v107, v106
	s_waitcnt lgkmcnt(1)
	s_mov_b32 m0, s8
	v_mfma_f32_16x16x32_bf16 v[32:35], v[110:113], v[114:117], v[32:35]
	global_load_lds_dwordx4 v[238:239], off
	s_add_i32 s6, s4, 1
	s_cmp_lg_u32 s4, 2
	s_cselect_b32 s4, s6, 0
	v_mfma_f32_16x16x32_bf16 v[28:31], v[110:113], v[118:121], v[28:31]
	s_add_i32 s5, s5, 1
	s_cmp_eq_u32 s5, 16
	v_mfma_f32_16x16x32_bf16 v[24:27], v[110:113], v[126:129], v[24:27]
	v_mfma_f32_16x16x32_bf16 v[20:23], v[110:113], v[130:133], v[20:23]
	ds_read_b128 v[110:113], v109
	s_waitcnt lgkmcnt(1)
	v_mfma_f32_16x16x32_bf16 v[16:19], v[122:125], v[114:117], v[16:19]
	s_mov_b32 m0, s9
	v_mfma_f32_16x16x32_bf16 v[12:15], v[122:125], v[118:121], v[12:15]
	global_load_lds_dwordx4 v[240:241], off
	v_mfma_f32_16x16x32_bf16 v[8:11], v[122:125], v[126:129], v[8:11]
	v_mfma_f32_16x16x32_bf16 v[2:5], v[122:125], v[130:133], v[2:5]
	ds_read_b128 v[114:117], v134 offset:32768
	ds_read_b128 v[118:121], v134 offset:34816
	ds_read_b128 v[122:125], v109 offset:2048
	ds_read_b128 v[126:129], v134 offset:36864
	ds_read_b128 v[130:133], v134 offset:38912
	s_waitcnt lgkmcnt(4)
	v_mfma_f32_16x16x32_bf16 v[64:67], v[110:113], v[114:117], v[64:67]
	s_waitcnt lgkmcnt(3)
	v_mfma_f32_16x16x32_bf16 v[60:63], v[110:113], v[118:121], v[60:63]
	s_waitcnt lgkmcnt(1)
	s_mov_b32 m0, s10
	v_mfma_f32_16x16x32_bf16 v[56:59], v[110:113], v[126:129], v[56:59]
	global_load_lds_dwordx4 v[242:243], off
	s_waitcnt lgkmcnt(0)
	v_mfma_f32_16x16x32_bf16 v[52:55], v[110:113], v[130:133], v[52:55]
	v_mfma_f32_16x16x32_bf16 v[48:51], v[122:125], v[114:117], v[48:51]
	v_mfma_f32_16x16x32_bf16 v[44:47], v[122:125], v[118:121], v[44:47]
	v_mfma_f32_16x16x32_bf16 v[40:43], v[122:125], v[126:129], v[40:43]
	s_mov_b32 m0, s11
	v_mfma_f32_16x16x32_bf16 v[36:39], v[122:125], v[130:133], v[36:39]
	global_load_lds_dwordx4 v[244:245], off
	ds_read_b128 v[110:113], v109 offset:4096
	ds_read_b128 v[122:125], v109 offset:6144
	s_waitcnt lgkmcnt(1)
	v_mfma_f32_16x16x32_bf16 v[32:35], v[110:113], v[114:117], v[32:35]
	v_mfma_f32_16x16x32_bf16 v[28:31], v[110:113], v[118:121], v[28:31]
	v_mfma_f32_16x16x32_bf16 v[24:27], v[110:113], v[126:129], v[24:27]
	v_mfma_f32_16x16x32_bf16 v[20:23], v[110:113], v[130:133], v[20:23]
	s_waitcnt lgkmcnt(0)
	s_mov_b32 m0, s12
	v_mfma_f32_16x16x32_bf16 v[16:19], v[122:125], v[114:117], v[16:19]
	global_load_lds_dwordx4 v[246:247], off
	s_mov_b32 m0, s13
	v_mfma_f32_16x16x32_bf16 v[12:15], v[122:125], v[118:121], v[12:15]
	v_mfma_f32_16x16x32_bf16 v[8:11], v[122:125], v[126:129], v[8:11]
	v_mfma_f32_16x16x32_bf16 v[2:5], v[122:125], v[130:133], v[2:5]
	s_cbranch_scc0 .LBB0_830
	s_setprio 0
	v_or_b32_e32 v80, s1, v75
	v_ashrrev_i32_e32 v81, 31, v80
	s_waitcnt vmcnt(0)
	v_add_u32_e32 v82, s0, v0
	v_lshl_add_u64 v[76:77], v[80:81], 1, s[76:77]
	s_waitcnt lgkmcnt(0)
	s_barrier
	v_mad_i64_i32 v[78:79], s[0:1], v82, s83, v[76:77]
	s_movk_i32 s0, 0xc90
	s_nop 0
	v_cmp_gt_i32_e32 vcc, s0, v80
	s_and_saveexec_b64 s[0:1], vcc
	s_cbranch_execz .LBB0_833
	v_bfe_u32 v81, v64, 16, 1
	v_add3_u32 v64, v64, v81, s96
	global_store_short_d16_hi v[78:79], v64, off
